# input rmsnorm pass: gain and both rows' scale loads requested at the loop head with the row data; MLA body B: P packs first and row-sum adds under the PV MFMAs (confirmed by amplified phase-repeat A/B
# baseline (speedup 1.0000x reference)
; __device__ __forceinline__ unsigned pk2(float lo, float hi) { return f2bf(lo) | (f2bf(hi) << 16); }
; __device__ __forceinline__ void phase_xs(Ctx& F, const float* xlat, const float* xctx, const float* g, const float* modl, float* ss1, bf16* XS) {
;     ...
;     for (int row0 = 2 * gw; row0 < MT; row0 += 2 * NGW) {
;         f32x4 v[2][4]; float ss[2] = {0.f, 0.f};
; #pragma unroll
;         for (int q = 0; q < 2; ++q) { const int row = row0 + q;
;             const float* xr = row < ML ? xlat + (size_t)row * DM : xctx + (size_t)(row - ML) * DM;
; #pragma unroll
;             for (int j = 0; j < 4; ++j) v[q][j] = __builtin_nontemporal_load((const f32x4*)(xr + 256 * j + 4 * lane)); }
; #pragma unroll
;         for (int q = 0; q < 2; ++q) { const int row = row0 + q; const int s = row < ML ? (row >> 13) : 4;
;             const float* sc = modl + s * MODW + DM;
; #pragma unroll
;             for (int j = 0; j < 4; ++j) ss[q] += (v[q][j][0] * v[q][j][0] + v[q][j][1] * v[q][j][1]) + (v[q][j][2] * v[q][j][2] + v[q][j][3] * v[q][j][3]);
;             ss[q] = wave_sum(ss[q]);
;             if (lane == 0) ss1[row] = ss[q];
; #pragma unroll
;             for (int j = 0; j < 4; ++j) { const int c = 256 * j + 4 * lane;
;                 const f32x4 gg = *(const f32x4*)(g + c), s1 = *(const f32x4*)(sc + c);
;                 const f32x4 y = v[q][j] * gg * (s1 + 1.0f);
;                 v2u w; w.x = pk2(y[0], y[1]); w.y = pk2(y[2], y[3]); *(v2u*)(XS + (size_t)row * DM + c) = w; } }
.LBB0_36:
	s_or_b64 exec, exec, s[0:1]
	s_and_b64 s[0:1], s[12:13], exec
	s_cselect_b32 s0, s20, 0x6000
	s_ashr_i32 s1, s0, 31
	s_lshl_b64 s[0:1], s[0:1], 2
	s_add_u32 s0, s62, s0
	s_addc_u32 s1, s63, s1
	s_add_u32 s0, s0, 0x1000
	s_addc_u32 s1, s1, 0
	s_waitcnt lgkmcnt(0)
	s_add_u32 s4, s4, s2
	s_addc_u32 s5, s5, s3
	s_add_u32 s6, s6, s8
	s_addc_u32 s7, s7, s9
	s_cmp_lt_i32 s4, 0x8400
	v_lshl_add_u64 v[34:35], v[34:35], 0, s[10:11]
	v_pk_mul_f32 v[14:15], v[14:15], v[98:99]
	v_pk_mul_f32 v[12:13], v[12:13], v[96:97]
	v_pk_add_f32 v[16:17], v[130:131], 1.0 op_sel_hi:[1, 0]
	v_pk_add_f32 v[18:19], v[128:129], 1.0 op_sel_hi:[1, 0]
	v_pk_mul_f32 v[14:15], v[14:15], v[16:17]
	v_pk_mul_f32 v[12:13], v[12:13], v[18:19]
	v_bfe_u32 v18, v14, 16, 1
	v_bfe_u32 v16, v12, 16, 1
	v_bfe_u32 v17, v13, 16, 1
	v_bfe_u32 v19, v15, 16, 1
	v_add3_u32 v12, v12, v16, s75
	v_add3_u32 v14, v14, v18, s75
	v_add3_u32 v13, v13, v17, s75
	v_add3_u32 v15, v15, v19, s75
	v_lshrrev_b32_e32 v12, 16, v12
	v_lshrrev_b32_e32 v14, 16, v14
	v_and_or_b32 v12, v13, s95, v12
	v_and_or_b32 v13, v15, s95, v14
	global_store_dwordx2 v[36:37], v[12:13], off offset:2048
	v_pk_mul_f32 v[10:11], v[10:11], v[102:103]
	v_pk_mul_f32 v[8:9], v[8:9], v[100:101]
	v_pk_add_f32 v[12:13], v[134:135], 1.0 op_sel_hi:[1, 0]
	v_pk_add_f32 v[14:15], v[132:133], 1.0 op_sel_hi:[1, 0]
	v_pk_mul_f32 v[10:11], v[10:11], v[12:13]
	v_pk_mul_f32 v[8:9], v[8:9], v[14:15]
	v_bfe_u32 v14, v10, 16, 1
	v_bfe_u32 v12, v8, 16, 1
	v_bfe_u32 v13, v9, 16, 1
	v_bfe_u32 v15, v11, 16, 1
	v_add3_u32 v8, v8, v12, s75
	v_add3_u32 v10, v10, v14, s75
	v_add3_u32 v9, v9, v13, s75
	v_add3_u32 v11, v11, v15, s75
	v_lshrrev_b32_e32 v8, 16, v8
	v_lshrrev_b32_e32 v10, 16, v10
	v_and_or_b32 v8, v9, s95, v8
	v_and_or_b32 v9, v11, s95, v10
	global_store_dwordx2 v[36:37], v[8:9], off offset:2560
	v_pk_mul_f32 v[6:7], v[6:7], v[106:107]
	v_pk_mul_f32 v[4:5], v[4:5], v[104:105]
	v_pk_add_f32 v[8:9], v[138:139], 1.0 op_sel_hi:[1, 0]
	v_pk_add_f32 v[10:11], v[136:137], 1.0 op_sel_hi:[1, 0]
	v_pk_mul_f32 v[6:7], v[6:7], v[8:9]
	v_pk_mul_f32 v[4:5], v[4:5], v[10:11]
	v_bfe_u32 v10, v6, 16, 1
	v_bfe_u32 v8, v4, 16, 1
	v_bfe_u32 v9, v5, 16, 1
	v_bfe_u32 v11, v7, 16, 1
	v_add3_u32 v4, v4, v8, s75
	v_add3_u32 v6, v6, v10, s75
	v_add3_u32 v5, v5, v9, s75
	v_add3_u32 v7, v7, v11, s75
	v_lshrrev_b32_e32 v4, 16, v4
	v_lshrrev_b32_e32 v6, 16, v6
	v_and_or_b32 v4, v5, s95, v4
	v_and_or_b32 v5, v7, s95, v6
	global_store_dwordx2 v[36:37], v[4:5], off offset:3072
	v_pk_mul_f32 v[2:3], v[2:3], v[110:111]
	v_pk_mul_f32 v[0:1], v[0:1], v[108:109]
	v_pk_add_f32 v[4:5], v[142:143], 1.0 op_sel_hi:[1, 0]
	v_pk_add_f32 v[6:7], v[140:141], 1.0 op_sel_hi:[1, 0]
	v_pk_mul_f32 v[2:3], v[2:3], v[4:5]
	v_pk_mul_f32 v[0:1], v[0:1], v[6:7]
	v_bfe_u32 v6, v2, 16, 1
	v_bfe_u32 v4, v0, 16, 1
	v_bfe_u32 v5, v1, 16, 1
	v_bfe_u32 v7, v3, 16, 1
	v_add3_u32 v0, v0, v4, s75
	v_add3_u32 v2, v2, v6, s75
	v_add3_u32 v1, v1, v5, s75
	v_add3_u32 v3, v3, v7, s75
	v_lshrrev_b32_e32 v0, 16, v0
	v_lshrrev_b32_e32 v2, 16, v2
	v_and_or_b32 v0, v1, s95, v0
	v_and_or_b32 v1, v3, s95, v2
	global_store_dwordx2 v[36:37], v[0:1], off offset:3584
	s_cbranch_scc0 .LBB0_41
.LBB0_37:
	s_add_i32 s14, s4, 0xffff8000
	s_cmp_lt_i32 s4, 0x8000
	s_cselect_b64 s[0:1], -1, 0
	s_and_b64 s[12:13], s[0:1], exec
	s_cselect_b32 s13, s5, 0
	s_cselect_b32 s12, s4, s14
	s_cselect_b32 s14, s17, s19
	s_cselect_b32 s15, s16, s18
	s_lshl_b64 s[12:13], s[12:13], 12
	s_add_u32 s12, s15, s12
	s_addc_u32 s13, s14, s13
	global_load_dwordx4 v[28:31], v44, s[12:13] nt
	global_load_dwordx4 v[24:27], v44, s[12:13] offset:1024 nt
	global_load_dwordx4 v[20:23], v44, s[12:13] offset:2048 nt
	global_load_dwordx4 v[16:19], v44, s[12:13] offset:3072 nt
	s_add_u32 s20, s4, 1
	s_addc_u32 s21, s5, 0
	s_add_i32 s22, s4, 0xffff8001
	s_cmp_lt_i32 s20, 0x8000
	s_cselect_b64 s[12:13], -1, 0
	s_and_b64 s[14:15], s[12:13], exec
	s_cselect_b32 s15, s21, 0
	s_cselect_b32 s14, s20, s22
	s_cselect_b32 s20, s17, s19
	s_cselect_b32 s21, s16, s18
	s_lshl_b64 s[14:15], s[14:15], 12
	s_add_u32 s14, s21, s14
	s_addc_u32 s15, s20, s15
	global_load_dwordx4 v[12:15], v44, s[14:15] nt
	global_load_dwordx4 v[8:11], v44, s[14:15] offset:1024 nt
	global_load_dwordx4 v[4:7], v44, s[14:15] offset:2048 nt
	global_load_dwordx4 v[0:3], v44, s[14:15] offset:3072 nt
	global_load_dwordx4 v[96:99], v[32:33], off
	global_load_dwordx4 v[100:103], v[32:33], off offset:1024
	global_load_dwordx4 v[104:107], v[32:33], off offset:2048
	global_load_dwordx4 v[108:111], v[32:33], off offset:3072
	s_ashr_i32 s98, s4, 13
	s_mulk_i32 s98, 0x1800
	s_cmp_lt_i32 s4, 0x8000
	s_cselect_b32 s98, s98, 0x6000
	s_ashr_i32 s99, s98, 31
	s_lshl_b64 s[98:99], s[98:99], 2
	s_add_u32 s98, s62, s98
	s_addc_u32 s99, s63, s99
	s_add_u32 s98, s98, 0x1000
	s_addc_u32 s99, s99, 0
	global_load_dwordx4 v[112:115], v44, s[98:99]
	global_load_dwordx4 v[116:119], v45, s[98:99]
	global_load_dwordx4 v[120:123], v46, s[98:99]
	global_load_dwordx4 v[124:127], v47, s[98:99]
	s_ashr_i32 s98, s4, 13
	s_mulk_i32 s98, 0x1800
	s_add_i32 s99, s4, 1
	s_cmp_lt_i32 s99, 0x8000
	s_cselect_b32 s98, s98, 0x6000
	s_ashr_i32 s99, s98, 31
	s_lshl_b64 s[98:99], s[98:99], 2
	s_add_u32 s98, s62, s98
	s_addc_u32 s99, s63, s99
	s_add_u32 s98, s98, 0x1000
	s_addc_u32 s99, s99, 0
	global_load_dwordx4 v[128:131], v44, s[98:99]
	global_load_dwordx4 v[132:135], v45, s[98:99]
	global_load_dwordx4 v[136:139], v46, s[98:99]
	global_load_dwordx4 v[140:143], v47, s[98:99]
	s_waitcnt vmcnt(0)
	v_mul_f32_e32 v36, v29, v29
	v_mul_f32_e32 v37, v31, v31
	s_waitcnt vmcnt(6)
	v_mul_f32_e32 v48, v25, v25
	v_mul_f32_e32 v49, v27, v27
	s_waitcnt vmcnt(5)
	v_mul_f32_e32 v50, v21, v21
	v_mul_f32_e32 v51, v23, v23
	v_fmac_f32_e32 v36, v28, v28
	v_fmac_f32_e32 v37, v30, v30
	v_fmac_f32_e32 v48, v24, v24
	v_fmac_f32_e32 v49, v26, v26
	s_waitcnt vmcnt(4)
	v_mul_f32_e32 v52, v17, v17
	v_mul_f32_e32 v53, v19, v19
	v_fmac_f32_e32 v50, v20, v20
	v_fmac_f32_e32 v51, v22, v22
	v_add_f32_e32 v36, v36, v37
	v_add_f32_e32 v37, v48, v49
	v_fmac_f32_e32 v52, v16, v16
	v_fmac_f32_e32 v53, v18, v18
	v_add_f32_e32 v48, v50, v51
	v_add_f32_e32 v36, v36, v37
	v_add_f32_e32 v36, v36, v48
	v_add_f32_e32 v37, v52, v53
	v_add_f32_e32 v36, v36, v37
	ds_bpermute_b32 v37, v38, v36
	s_waitcnt lgkmcnt(0)
	v_add_f32_e32 v36, v36, v37
	ds_bpermute_b32 v37, v39, v36
	s_waitcnt lgkmcnt(0)
	v_add_f32_e32 v36, v36, v37
	ds_bpermute_b32 v37, v40, v36
	s_waitcnt lgkmcnt(0)
	v_add_f32_e32 v36, v36, v37
	ds_bpermute_b32 v37, v41, v36
	s_waitcnt lgkmcnt(0)
	v_add_f32_e32 v36, v36, v37
	ds_bpermute_b32 v37, v42, v36
	s_waitcnt lgkmcnt(0)
	v_add_f32_e32 v36, v36, v37
	ds_bpermute_b32 v37, v43, v36
	s_and_saveexec_b64 s[14:15], vcc
	s_cbranch_execz .LBB0_39
	s_add_u32 s20, s62, s6
	s_waitcnt lgkmcnt(0)
	v_add_f32_e32 v36, v36, v37
	s_addc_u32 s21, s63, s7
	global_store_dword v245, v36, s[20:21]
; __device__ __forceinline__ unsigned pk2(float lo, float hi) { return f2bf(lo) | (f2bf(hi) << 16); }
; __device__ __forceinline__ void phase_xs(Ctx& F, const float* xlat, const float* xctx, const float* g, const float* modl, float* ss1, bf16* XS) {
;     ...
;         for (int q = 0; q < 2; ++q) { const int row = row0 + q; const int s = row < ML ? (row >> 13) : 4;
;             const float* sc = modl + s * MODW + DM;
; #pragma unroll
;             for (int j = 0; j < 4; ++j) ss[q] += (v[q][j][0] * v[q][j][0] + v[q][j][1] * v[q][j][1]) + (v[q][j][2] * v[q][j][2] + v[q][j][3] * v[q][j][3]);
;             ss[q] = wave_sum(ss[q]);
;             if (lane == 0) ss1[row] = ss[q];
; #pragma unroll
;             for (int j = 0; j < 4; ++j) { const int c = 256 * j + 4 * lane;
;                 const f32x4 gg = *(const f32x4*)(g + c), s1 = *(const f32x4*)(sc + c);
;                 const f32x4 y = v[q][j] * gg * (s1 + 1.0f);
;                 v2u w; w.x = pk2(y[0], y[1]); w.y = pk2(y[2], y[3]); *(v2u*)(XS + (size_t)row * DM + c) = w; } }
.LBB0_39:
	s_or_b64 exec, exec, s[14:15]
	s_ashr_i32 s20, s4, 13
	s_mulk_i32 s20, 0x1800
	s_and_b64 s[0:1], s[0:1], exec
	s_cselect_b32 s0, s20, 0x6000
	s_ashr_i32 s1, s0, 31
	s_lshl_b64 s[0:1], s[0:1], 2
	s_add_u32 s0, s62, s0
	s_addc_u32 s1, s63, s1
	s_add_u32 s14, s0, 0x1000
	s_addc_u32 s15, s1, 0
	s_waitcnt lgkmcnt(0)
	v_lshl_add_u64 v[36:37], s[62:63], 0, v[34:35]
	s_mov_b32 s0, 0x3400000
	v_add_co_u32_e64 v36, s[0:1], s0, v36
	v_pk_mul_f32 v[30:31], v[30:31], v[98:99]
	v_pk_mul_f32 v[28:29], v[28:29], v[96:97]
	v_pk_add_f32 v[48:49], v[114:115], 1.0 op_sel_hi:[1, 0]
	v_pk_add_f32 v[50:51], v[112:113], 1.0 op_sel_hi:[1, 0]
	v_pk_mul_f32 v[30:31], v[30:31], v[48:49]
	v_pk_mul_f32 v[28:29], v[28:29], v[50:51]
	v_bfe_u32 v50, v30, 16, 1
	v_bfe_u32 v48, v28, 16, 1
	v_bfe_u32 v49, v29, 16, 1
	v_bfe_u32 v51, v31, 16, 1
	v_add3_u32 v28, v28, v48, s75
	v_add3_u32 v30, v30, v50, s75
	v_add3_u32 v29, v29, v49, s75
	v_add3_u32 v31, v31, v51, s75
	v_lshrrev_b32_e32 v28, 16, v28
	v_lshrrev_b32_e32 v30, 16, v30
	v_addc_co_u32_e64 v37, s[0:1], 0, v37, s[0:1]
	v_and_or_b32 v28, v29, s95, v28
	v_and_or_b32 v29, v31, s95, v30
	global_store_dwordx2 v[36:37], v[28:29], off
	v_pk_mul_f32 v[26:27], v[26:27], v[102:103]
	v_pk_mul_f32 v[24:25], v[24:25], v[100:101]
	v_pk_add_f32 v[28:29], v[118:119], 1.0 op_sel_hi:[1, 0]
	v_pk_add_f32 v[30:31], v[116:117], 1.0 op_sel_hi:[1, 0]
	v_pk_mul_f32 v[26:27], v[26:27], v[28:29]
	v_pk_mul_f32 v[24:25], v[24:25], v[30:31]
	v_bfe_u32 v30, v26, 16, 1
	v_bfe_u32 v28, v24, 16, 1
	v_bfe_u32 v29, v25, 16, 1
	v_bfe_u32 v31, v27, 16, 1
	v_add3_u32 v24, v24, v28, s75
	v_add3_u32 v26, v26, v30, s75
	v_add3_u32 v25, v25, v29, s75
	v_add3_u32 v27, v27, v31, s75
	v_lshrrev_b32_e32 v24, 16, v24
	v_lshrrev_b32_e32 v26, 16, v26
	v_and_or_b32 v24, v25, s95, v24
	v_and_or_b32 v25, v27, s95, v26
	global_store_dwordx2 v[36:37], v[24:25], off offset:512
	v_mul_f32_e32 v48, v5, v5
	v_mul_f32_e32 v49, v7, v7
	v_mul_f32_e32 v50, v1, v1
	v_mul_f32_e32 v51, v3, v3
	v_fmac_f32_e32 v48, v4, v4
	v_fmac_f32_e32 v49, v6, v6
	v_fmac_f32_e32 v50, v0, v0
	v_fmac_f32_e32 v51, v2, v2
	v_pk_mul_f32 v[22:23], v[22:23], v[106:107]
	v_pk_mul_f32 v[20:21], v[20:21], v[104:105]
	v_pk_add_f32 v[24:25], v[122:123], 1.0 op_sel_hi:[1, 0]
	v_pk_add_f32 v[26:27], v[120:121], 1.0 op_sel_hi:[1, 0]
	v_pk_mul_f32 v[22:23], v[22:23], v[24:25]
	v_pk_mul_f32 v[20:21], v[20:21], v[26:27]
	v_bfe_u32 v26, v22, 16, 1
	v_bfe_u32 v24, v20, 16, 1
	v_bfe_u32 v25, v21, 16, 1
	v_bfe_u32 v27, v23, 16, 1
	v_add3_u32 v20, v20, v24, s75
	v_add3_u32 v22, v22, v26, s75
	v_add3_u32 v21, v21, v25, s75
	v_add3_u32 v23, v23, v27, s75
	v_lshrrev_b32_e32 v20, 16, v20
	v_lshrrev_b32_e32 v22, 16, v22
	v_and_or_b32 v20, v21, s95, v20
	v_and_or_b32 v21, v23, s95, v22
	global_store_dwordx2 v[36:37], v[20:21], off offset:1024
	v_mul_f32_e32 v20, v13, v13
	v_mul_f32_e32 v21, v15, v15
	v_mul_f32_e32 v30, v9, v9
	v_mul_f32_e32 v31, v11, v11
	v_fmac_f32_e32 v20, v12, v12
	v_fmac_f32_e32 v21, v14, v14
	v_fmac_f32_e32 v30, v8, v8
	v_fmac_f32_e32 v31, v10, v10
	v_add_f32_e32 v20, v20, v21
	v_add_f32_e32 v21, v30, v31
	v_add_f32_e32 v30, v48, v49
	v_add_f32_e32 v20, v20, v21
	v_add_f32_e32 v31, v50, v51
	v_add_f32_e32 v20, v20, v30
	v_add_f32_e32 v20, v20, v31
	ds_bpermute_b32 v21, v38, v20
	s_waitcnt lgkmcnt(0)
	v_add_f32_e32 v20, v20, v21
	ds_bpermute_b32 v21, v39, v20
	s_waitcnt lgkmcnt(0)
	v_add_f32_e32 v20, v20, v21
	ds_bpermute_b32 v21, v40, v20
	s_waitcnt lgkmcnt(0)
	v_add_f32_e32 v20, v20, v21
	ds_bpermute_b32 v21, v41, v20
	s_waitcnt lgkmcnt(0)
	v_add_f32_e32 v20, v20, v21
	ds_bpermute_b32 v21, v42, v20
	s_waitcnt lgkmcnt(0)
	v_add_f32_e32 v20, v20, v21
	ds_bpermute_b32 v21, v43, v20
	v_pk_mul_f32 v[18:19], v[18:19], v[110:111]
	v_pk_mul_f32 v[16:17], v[16:17], v[108:109]
	v_pk_add_f32 v[22:23], v[126:127], 1.0 op_sel_hi:[1, 0]
	v_pk_add_f32 v[24:25], v[124:125], 1.0 op_sel_hi:[1, 0]
	v_pk_mul_f32 v[18:19], v[18:19], v[22:23]
	v_pk_mul_f32 v[16:17], v[16:17], v[24:25]
	v_bfe_u32 v24, v18, 16, 1
	v_bfe_u32 v22, v16, 16, 1
	v_bfe_u32 v23, v17, 16, 1
	v_bfe_u32 v25, v19, 16, 1
	v_add3_u32 v16, v16, v22, s75
	v_add3_u32 v18, v18, v24, s75
	v_add3_u32 v17, v17, v23, s75
	v_add3_u32 v19, v19, v25, s75
	v_lshrrev_b32_e32 v16, 16, v16
	v_lshrrev_b32_e32 v18, 16, v18
	v_and_or_b32 v16, v17, s95, v16
	v_and_or_b32 v17, v19, s95, v18
	global_store_dwordx2 v[36:37], v[16:17], off offset:1536
	s_and_saveexec_b64 s[0:1], vcc
	s_cbranch_execz .LBB0_36
	s_add_u32 s14, s62, s6
	s_waitcnt lgkmcnt(0)
	v_add_f32_e32 v16, v20, v21
	s_addc_u32 s15, s63, s7
	global_store_dword v245, v16, s[14:15] offset:4
	s_branch .LBB0_36
